# v21 plus: grid barrier early acquire, the L1 invalidate is issued at arrival (behind the arrival atomic) and overlaps the wait; late invalidates removed, every path still waits vmcnt(0) before the clo
# speedup vs baseline: 1.0097x; 1.0020x over previous
; __device__ __forceinline__ unsigned xb_ld(unsigned* p)              { return __hip_atomic_load(p, __ATOMIC_RELAXED, __HIP_MEMORY_SCOPE_AGENT); }
; __device__ __forceinline__ unsigned xb_add(unsigned* p, unsigned v) { return __hip_atomic_fetch_add(p, v, __ATOMIC_RELAXED, __HIP_MEMORY_SCOPE_AGENT); }
; #define XB_SPIN(cond, bar) do { unsigned _sp = 0; while (cond) { __builtin_amdgcn_s_sleep(1); \
;     if ((++_sp & 255u) == 0u) { if (xb_ld(&(bar)[XB_TMO])) break; if (_sp > XB_SPIN_CAP) { atomicAdd(&(bar)[XB_TMO], 1u); break; } } } } while (0)
; __device__ __forceinline__ void xcd_barrier(const XcdBarrier& b) {
;     ...
;         unsigned nloc = b.st[0], nx = b.st[1];
;         if (nloc == 0u) { xcd_barrier_complete(bar, b.x, nloc, nx); b.st[0] = nloc; b.st[1] = nx; }
;         const unsigned old = xb_add(&bar[XB_XSUB(b.x)], 1u);
;         const unsigned gen = old / nloc;
;         if (old + 1u == (gen + 1u) * nloc) {
;             __builtin_amdgcn_fence(__ATOMIC_RELEASE, "agent");
;             asm volatile("s_waitcnt vmcnt(0)" ::: "memory");
;             const unsigned og = xb_add(&bar[XB_TOP], 1u);
;             const unsigned tg = og / nx;
;             if (og + 1u == (tg + 1u) * nx) xb_add(&bar[XB_TOPGEN], 1u);
;             else XB_SPIN(xb_ld(&bar[XB_TOPGEN]) == tg, bar);
;             __builtin_amdgcn_fence(__ATOMIC_ACQUIRE, "agent");
;             xb_add(&bar[XB_XGEN(b.x)], 1u);
;             asm volatile("s_waitcnt vmcnt(0)" ::: "memory");
;         } else {
;             XB_SPIN(xb_ld(&bar[XB_XGEN(b.x)]) == gen, bar);
;             __builtin_amdgcn_fence(__ATOMIC_ACQUIRE, "agent");
.LBB0_117:
	s_or_b64 exec, exec, s[14:15]
	buffer_inv sc1
	v_cvt_f32_u32_e32 v4, v2
	s_waitcnt vmcnt(1)
	v_readfirstlane_b32 s12, v3
	v_sub_u32_e32 v3, 0, v2
	v_rcp_iflag_f32_e32 v4, v4
	v_add_u32_e32 v5, s12, v1
	v_mul_f32_e32 v4, 0x4f7ffffe, v4
	v_cvt_u32_f32_e32 v4, v4
	v_mul_lo_u32 v1, v3, v4
	v_mul_hi_u32 v1, v4, v1
	v_add_u32_e32 v1, v4, v1
	v_mul_hi_u32 v1, v5, v1
	v_mul_lo_u32 v3, v1, v2
	v_sub_u32_e32 v3, v5, v3
	v_add_u32_e32 v4, 1, v1
	v_cmp_ge_u32_e32 vcc, v3, v2
	s_nop 1
	v_cndmask_b32_e32 v1, v1, v4, vcc
	v_sub_u32_e32 v4, v3, v2
	v_cndmask_b32_e32 v3, v3, v4, vcc
	v_add_u32_e32 v4, 1, v1
	v_cmp_ge_u32_e32 vcc, v3, v2
	v_add_u32_e32 v3, 1, v5
	s_nop 0
	v_cndmask_b32_e32 v1, v1, v4, vcc
	v_mul_lo_u32 v4, v2, v1
	v_add_u32_e32 v2, v4, v2
	v_cmp_ne_u32_e32 vcc, v3, v2
	s_and_saveexec_b64 s[12:13], vcc
	s_xor_b64 s[12:13], exec, s[12:13]
	s_cbranch_execz .LBB0_131
	s_waitcnt lgkmcnt(0)
	v_mov_b32_e32 v0, 0x2000
	global_load_dword v0, v0, s[10:11] offset:1024 sc1
	s_add_u32 s18, s10, 0x2400
	s_addc_u32 s19, s11, 0
	s_waitcnt vmcnt(0)
	v_cmp_eq_u32_e32 vcc, v0, v1
	s_and_saveexec_b64 s[14:15], vcc
	s_cbranch_execz .LBB0_130
	s_add_u32 s16, s24, 0x4200
	s_addc_u32 s17, s25, 0
	s_mov_b32 s33, 1
	s_mov_b64 s[20:21], 0
	v_mov_b32_e32 v0, 0
	s_branch .LBB0_121

; __device__ __forceinline__ unsigned xb_ld(unsigned* p)              { return __hip_atomic_load(p, __ATOMIC_RELAXED, __HIP_MEMORY_SCOPE_AGENT); }
; #define XB_SPIN(cond, bar) do { unsigned _sp = 0; while (cond) { __builtin_amdgcn_s_sleep(1); \
;     if ((++_sp & 255u) == 0u) { if (xb_ld(&(bar)[XB_TMO])) break; if (_sp > XB_SPIN_CAP) { atomicAdd(&(bar)[XB_TMO], 1u); break; } } } } while (0)
; __device__ __forceinline__ void xcd_barrier(const XcdBarrier& b) {
;     ...
;             XB_SPIN(xb_ld(&bar[XB_XGEN(b.x)]) == gen, bar);
;             __builtin_amdgcn_fence(__ATOMIC_ACQUIRE, "agent");
;             asm volatile("s_waitcnt vmcnt(0)" ::: "memory");
.LBB0_130:
	s_or_b64 exec, exec, s[14:15]
	s_waitcnt vmcnt(0)
	s_waitcnt vmcnt(0)

; __device__ __forceinline__ unsigned xb_add(unsigned* p, unsigned v) { return __hip_atomic_fetch_add(p, v, __ATOMIC_RELAXED, __HIP_MEMORY_SCOPE_AGENT); }
; __device__ __forceinline__ void xcd_barrier(const XcdBarrier& b) {
;     ...
;             __builtin_amdgcn_fence(__ATOMIC_ACQUIRE, "agent");
;             xb_add(&bar[XB_XGEN(b.x)], 1u);
;             asm volatile("s_waitcnt vmcnt(0)" ::: "memory");
.LBB0_148:
	s_or_b64 exec, exec, s[12:13]
	s_mov_b64 s[12:13], exec
	v_mbcnt_lo_u32_b32 v0, s12, 0
	v_mbcnt_hi_u32_b32 v0, s13, v0
	v_cmp_eq_u32_e32 vcc, 0, v0
	s_waitcnt vmcnt(0)
	s_and_saveexec_b64 s[14:15], vcc
	s_cbranch_execz .LBB0_150
	s_bcnt1_i32_b64 s12, s[12:13]
	v_mov_b32_e32 v0, 0x2000
	v_mov_b32_e32 v1, s12
	global_atomic_add v0, v1, s[10:11] offset:1024

; __device__ __forceinline__ unsigned xb_ld(unsigned* p)              { return __hip_atomic_load(p, __ATOMIC_RELAXED, __HIP_MEMORY_SCOPE_AGENT); }
; __device__ __forceinline__ unsigned xb_add(unsigned* p, unsigned v) { return __hip_atomic_fetch_add(p, v, __ATOMIC_RELAXED, __HIP_MEMORY_SCOPE_AGENT); }
; #define XB_SPIN(cond, bar) do { unsigned _sp = 0; while (cond) { __builtin_amdgcn_s_sleep(1); \
;     if ((++_sp & 255u) == 0u) { if (xb_ld(&(bar)[XB_TMO])) break; if (_sp > XB_SPIN_CAP) { atomicAdd(&(bar)[XB_TMO], 1u); break; } } } } while (0)
; __device__ __forceinline__ void xcd_barrier(const XcdBarrier& b) {
;     ...
;         unsigned nloc = b.st[0], nx = b.st[1];
;         if (nloc == 0u) { xcd_barrier_complete(bar, b.x, nloc, nx); b.st[0] = nloc; b.st[1] = nx; }
;         const unsigned old = xb_add(&bar[XB_XSUB(b.x)], 1u);
;         const unsigned gen = old / nloc;
;         if (old + 1u == (gen + 1u) * nloc) {
;             __builtin_amdgcn_fence(__ATOMIC_RELEASE, "agent");
;             asm volatile("s_waitcnt vmcnt(0)" ::: "memory");
;             const unsigned og = xb_add(&bar[XB_TOP], 1u);
;             const unsigned tg = og / nx;
;             if (og + 1u == (tg + 1u) * nx) xb_add(&bar[XB_TOPGEN], 1u);
;             else XB_SPIN(xb_ld(&bar[XB_TOPGEN]) == tg, bar);
;             __builtin_amdgcn_fence(__ATOMIC_ACQUIRE, "agent");
;             xb_add(&bar[XB_XGEN(b.x)], 1u);
;             asm volatile("s_waitcnt vmcnt(0)" ::: "memory");
;         } else {
;             XB_SPIN(xb_ld(&bar[XB_XGEN(b.x)]) == gen, bar);
;             __builtin_amdgcn_fence(__ATOMIC_ACQUIRE, "agent");
.LBB0_328:
	s_or_b64 exec, exec, s[12:13]
	buffer_inv sc1
	v_cvt_f32_u32_e32 v4, v2
	s_waitcnt vmcnt(1)
	v_readfirstlane_b32 s10, v3
	v_sub_u32_e32 v3, 0, v2
	v_rcp_iflag_f32_e32 v4, v4
	v_add_u32_e32 v5, s10, v1
	v_mul_f32_e32 v4, 0x4f7ffffe, v4
	v_cvt_u32_f32_e32 v4, v4
	v_mul_lo_u32 v1, v3, v4
	v_mul_hi_u32 v1, v4, v1
	v_add_u32_e32 v1, v4, v1
	v_mul_hi_u32 v1, v5, v1
	v_mul_lo_u32 v3, v1, v2
	v_sub_u32_e32 v3, v5, v3
	v_add_u32_e32 v4, 1, v1
	v_cmp_ge_u32_e32 vcc, v3, v2
	s_nop 1
	v_cndmask_b32_e32 v1, v1, v4, vcc
	v_sub_u32_e32 v4, v3, v2
	v_cndmask_b32_e32 v3, v3, v4, vcc
	v_add_u32_e32 v4, 1, v1
	v_cmp_ge_u32_e32 vcc, v3, v2
	v_add_u32_e32 v3, 1, v5
	s_nop 0
	v_cndmask_b32_e32 v1, v1, v4, vcc
	v_mul_lo_u32 v4, v2, v1
	v_add_u32_e32 v2, v4, v2
	v_cmp_ne_u32_e32 vcc, v3, v2
	s_and_saveexec_b64 s[10:11], vcc
	s_xor_b64 s[10:11], exec, s[10:11]
	s_cbranch_execz .LBB0_342
	s_waitcnt lgkmcnt(0)
	v_mov_b32_e32 v0, 0x2000
	global_load_dword v0, v0, s[8:9] offset:1024 sc1
	s_add_u32 s16, s8, 0x2400
	s_addc_u32 s17, s9, 0
	s_waitcnt vmcnt(0)
	v_cmp_eq_u32_e32 vcc, v0, v1
	s_and_saveexec_b64 s[12:13], vcc
	s_cbranch_execz .LBB0_341
	s_add_u32 s14, s24, 0x4200
	s_addc_u32 s15, s25, 0
	s_mov_b32 s30, 1
	s_mov_b64 s[18:19], 0
	v_mov_b32_e32 v0, 0
	s_branch .LBB0_332

; __device__ __forceinline__ unsigned xb_ld(unsigned* p)              { return __hip_atomic_load(p, __ATOMIC_RELAXED, __HIP_MEMORY_SCOPE_AGENT); }
; #define XB_SPIN(cond, bar) do { unsigned _sp = 0; while (cond) { __builtin_amdgcn_s_sleep(1); \
;     if ((++_sp & 255u) == 0u) { if (xb_ld(&(bar)[XB_TMO])) break; if (_sp > XB_SPIN_CAP) { atomicAdd(&(bar)[XB_TMO], 1u); break; } } } } while (0)
; __device__ __forceinline__ void xcd_barrier(const XcdBarrier& b) {
;     ...
;             XB_SPIN(xb_ld(&bar[XB_XGEN(b.x)]) == gen, bar);
;             __builtin_amdgcn_fence(__ATOMIC_ACQUIRE, "agent");
;             asm volatile("s_waitcnt vmcnt(0)" ::: "memory");
.LBB0_341:
	s_or_b64 exec, exec, s[12:13]
	s_waitcnt vmcnt(0)
	s_waitcnt vmcnt(0)

; __device__ __forceinline__ unsigned xb_add(unsigned* p, unsigned v) { return __hip_atomic_fetch_add(p, v, __ATOMIC_RELAXED, __HIP_MEMORY_SCOPE_AGENT); }
; __device__ __forceinline__ void xcd_barrier(const XcdBarrier& b) {
;     ...
;             __builtin_amdgcn_fence(__ATOMIC_ACQUIRE, "agent");
;             xb_add(&bar[XB_XGEN(b.x)], 1u);
;             asm volatile("s_waitcnt vmcnt(0)" ::: "memory");
.LBB0_359:
	s_or_b64 exec, exec, s[10:11]
	s_mov_b64 s[10:11], exec
	v_mbcnt_lo_u32_b32 v0, s10, 0
	v_mbcnt_hi_u32_b32 v0, s11, v0
	v_cmp_eq_u32_e32 vcc, 0, v0
	s_waitcnt vmcnt(0)
	s_and_saveexec_b64 s[12:13], vcc
	s_cbranch_execz .LBB0_361
	s_bcnt1_i32_b64 s10, s[10:11]
	v_mov_b32_e32 v0, 0x2000
	v_mov_b32_e32 v1, s10
	global_atomic_add v0, v1, s[8:9] offset:1024

; __device__ __forceinline__ unsigned xb_ld(unsigned* p)              { return __hip_atomic_load(p, __ATOMIC_RELAXED, __HIP_MEMORY_SCOPE_AGENT); }
; __device__ __forceinline__ unsigned xb_add(unsigned* p, unsigned v) { return __hip_atomic_fetch_add(p, v, __ATOMIC_RELAXED, __HIP_MEMORY_SCOPE_AGENT); }
; #define XB_SPIN(cond, bar) do { unsigned _sp = 0; while (cond) { __builtin_amdgcn_s_sleep(1); \
;     if ((++_sp & 255u) == 0u) { if (xb_ld(&(bar)[XB_TMO])) break; if (_sp > XB_SPIN_CAP) { atomicAdd(&(bar)[XB_TMO], 1u); break; } } } } while (0)
; __device__ __forceinline__ void xcd_barrier(const XcdBarrier& b) {
;     ...
;         unsigned nloc = b.st[0], nx = b.st[1];
;         if (nloc == 0u) { xcd_barrier_complete(bar, b.x, nloc, nx); b.st[0] = nloc; b.st[1] = nx; }
;         const unsigned old = xb_add(&bar[XB_XSUB(b.x)], 1u);
;         const unsigned gen = old / nloc;
;         if (old + 1u == (gen + 1u) * nloc) {
;             __builtin_amdgcn_fence(__ATOMIC_RELEASE, "agent");
;             asm volatile("s_waitcnt vmcnt(0)" ::: "memory");
;             const unsigned og = xb_add(&bar[XB_TOP], 1u);
;             const unsigned tg = og / nx;
;             if (og + 1u == (tg + 1u) * nx) xb_add(&bar[XB_TOPGEN], 1u);
;             else XB_SPIN(xb_ld(&bar[XB_TOPGEN]) == tg, bar);
;             __builtin_amdgcn_fence(__ATOMIC_ACQUIRE, "agent");
;             xb_add(&bar[XB_XGEN(b.x)], 1u);
;             asm volatile("s_waitcnt vmcnt(0)" ::: "memory");
;         } else {
;             XB_SPIN(xb_ld(&bar[XB_XGEN(b.x)]) == gen, bar);
;             __builtin_amdgcn_fence(__ATOMIC_ACQUIRE, "agent");
.LBB0_419:
	s_or_b64 exec, exec, s[22:23]
	buffer_inv sc1
	v_cvt_f32_u32_e32 v4, v2
	s_waitcnt vmcnt(1)
	v_readfirstlane_b32 s11, v3
	v_sub_u32_e32 v3, 0, v2
	v_rcp_iflag_f32_e32 v4, v4
	v_add_u32_e32 v5, s11, v1
	v_mul_f32_e32 v4, 0x4f7ffffe, v4
	v_cvt_u32_f32_e32 v4, v4
	v_mul_lo_u32 v1, v3, v4
	v_mul_hi_u32 v1, v4, v1
	v_add_u32_e32 v1, v4, v1
	v_mul_hi_u32 v1, v5, v1
	v_mul_lo_u32 v3, v1, v2
	v_sub_u32_e32 v3, v5, v3
	v_add_u32_e32 v4, 1, v1
	v_cmp_ge_u32_e32 vcc, v3, v2
	s_nop 1
	v_cndmask_b32_e32 v1, v1, v4, vcc
	v_sub_u32_e32 v4, v3, v2
	v_cndmask_b32_e32 v3, v3, v4, vcc
	v_add_u32_e32 v4, 1, v1
	v_cmp_ge_u32_e32 vcc, v3, v2
	v_add_u32_e32 v3, 1, v5
	s_nop 0
	v_cndmask_b32_e32 v1, v1, v4, vcc
	v_mul_lo_u32 v4, v2, v1
	v_add_u32_e32 v2, v4, v2
	v_cmp_ne_u32_e32 vcc, v3, v2
	s_and_saveexec_b64 s[12:13], vcc
	s_xor_b64 s[22:23], exec, s[12:13]
	s_cbranch_execz .LBB0_433
	v_readlane_b32 s12, v247, 11
	v_readlane_b32 s13, v247, 12
	s_waitcnt lgkmcnt(0)
	s_nop 3
	global_load_dword v0, v173, s[12:13] sc1
	s_waitcnt vmcnt(0)
	v_cmp_eq_u32_e32 vcc, v0, v1
	s_and_saveexec_b64 s[28:29], vcc
	s_cbranch_execz .LBB0_432
	s_mov_b32 s11, 1
	s_mov_b64 s[36:37], 0
	s_branch .LBB0_423

; __device__ __forceinline__ unsigned xb_ld(unsigned* p)              { return __hip_atomic_load(p, __ATOMIC_RELAXED, __HIP_MEMORY_SCOPE_AGENT); }
; #define XB_SPIN(cond, bar) do { unsigned _sp = 0; while (cond) { __builtin_amdgcn_s_sleep(1); \
;     if ((++_sp & 255u) == 0u) { if (xb_ld(&(bar)[XB_TMO])) break; if (_sp > XB_SPIN_CAP) { atomicAdd(&(bar)[XB_TMO], 1u); break; } } } } while (0)
; __device__ __forceinline__ void xcd_barrier(const XcdBarrier& b) {
;     ...
;             XB_SPIN(xb_ld(&bar[XB_XGEN(b.x)]) == gen, bar);
;             __builtin_amdgcn_fence(__ATOMIC_ACQUIRE, "agent");
;             asm volatile("s_waitcnt vmcnt(0)" ::: "memory");
.LBB0_432:
	s_or_b64 exec, exec, s[28:29]
	s_waitcnt vmcnt(0)
	s_waitcnt vmcnt(0)

; __device__ __forceinline__ unsigned xb_add(unsigned* p, unsigned v) { return __hip_atomic_fetch_add(p, v, __ATOMIC_RELAXED, __HIP_MEMORY_SCOPE_AGENT); }
; __device__ __forceinline__ void xcd_barrier(const XcdBarrier& b) {
;     ...
;             __builtin_amdgcn_fence(__ATOMIC_ACQUIRE, "agent");
;             xb_add(&bar[XB_XGEN(b.x)], 1u);
;             asm volatile("s_waitcnt vmcnt(0)" ::: "memory");
.LBB0_450:
	s_or_b64 exec, exec, s[22:23]
	s_mov_b64 s[22:23], exec
	v_mbcnt_lo_u32_b32 v0, s22, 0
	v_mbcnt_hi_u32_b32 v0, s23, v0
	v_cmp_eq_u32_e32 vcc, 0, v0
	s_waitcnt vmcnt(0)
	s_and_saveexec_b64 s[28:29], vcc
	s_cbranch_execz .LBB0_452
	s_bcnt1_i32_b64 s11, s[22:23]
	v_readlane_b32 s12, v247, 11
	v_mov_b32_e32 v0, s11
	v_readlane_b32 s13, v247, 12
	s_nop 4
	global_atomic_add v173, v0, s[12:13]

; __device__ __forceinline__ unsigned xb_ld(unsigned* p)              { return __hip_atomic_load(p, __ATOMIC_RELAXED, __HIP_MEMORY_SCOPE_AGENT); }
; __device__ __forceinline__ unsigned xb_add(unsigned* p, unsigned v) { return __hip_atomic_fetch_add(p, v, __ATOMIC_RELAXED, __HIP_MEMORY_SCOPE_AGENT); }
; #define XB_SPIN(cond, bar) do { unsigned _sp = 0; while (cond) { __builtin_amdgcn_s_sleep(1); \
;     if ((++_sp & 255u) == 0u) { if (xb_ld(&(bar)[XB_TMO])) break; if (_sp > XB_SPIN_CAP) { atomicAdd(&(bar)[XB_TMO], 1u); break; } } } } while (0)
; __device__ __forceinline__ void xcd_barrier(const XcdBarrier& b) {
;     ...
;         unsigned nloc = b.st[0], nx = b.st[1];
;         if (nloc == 0u) { xcd_barrier_complete(bar, b.x, nloc, nx); b.st[0] = nloc; b.st[1] = nx; }
;         const unsigned old = xb_add(&bar[XB_XSUB(b.x)], 1u);
;         const unsigned gen = old / nloc;
;         if (old + 1u == (gen + 1u) * nloc) {
;             __builtin_amdgcn_fence(__ATOMIC_RELEASE, "agent");
;             asm volatile("s_waitcnt vmcnt(0)" ::: "memory");
;             const unsigned og = xb_add(&bar[XB_TOP], 1u);
;             const unsigned tg = og / nx;
;             if (og + 1u == (tg + 1u) * nx) xb_add(&bar[XB_TOPGEN], 1u);
;             else XB_SPIN(xb_ld(&bar[XB_TOPGEN]) == tg, bar);
;             __builtin_amdgcn_fence(__ATOMIC_ACQUIRE, "agent");
;             xb_add(&bar[XB_XGEN(b.x)], 1u);
;             asm volatile("s_waitcnt vmcnt(0)" ::: "memory");
;         } else {
;             XB_SPIN(xb_ld(&bar[XB_XGEN(b.x)]) == gen, bar);
;             __builtin_amdgcn_fence(__ATOMIC_ACQUIRE, "agent");
.LBB0_1389:
	s_or_b64 exec, exec, s[22:23]
	buffer_inv sc1
	v_cvt_f32_u32_e32 v4, v2
	s_waitcnt vmcnt(1)
	v_readfirstlane_b32 s6, v3
	v_sub_u32_e32 v3, 0, v2
	v_rcp_iflag_f32_e32 v4, v4
	v_add_u32_e32 v5, s6, v1
	v_mul_f32_e32 v4, 0x4f7ffffe, v4
	v_cvt_u32_f32_e32 v4, v4
	v_mul_lo_u32 v1, v3, v4
	v_mul_hi_u32 v1, v4, v1
	v_add_u32_e32 v1, v4, v1
	v_mul_hi_u32 v1, v5, v1
	v_mul_lo_u32 v3, v1, v2
	v_sub_u32_e32 v3, v5, v3
	v_add_u32_e32 v4, 1, v1
	v_cmp_ge_u32_e32 vcc, v3, v2
	s_nop 1
	v_cndmask_b32_e32 v1, v1, v4, vcc
	v_sub_u32_e32 v4, v3, v2
	v_cndmask_b32_e32 v3, v3, v4, vcc
	v_add_u32_e32 v4, 1, v1
	v_cmp_ge_u32_e32 vcc, v3, v2
	v_add_u32_e32 v3, 1, v5
	s_nop 0
	v_cndmask_b32_e32 v1, v1, v4, vcc
	v_mul_lo_u32 v4, v2, v1
	v_add_u32_e32 v2, v4, v2
	v_cmp_ne_u32_e32 vcc, v3, v2
	s_and_saveexec_b64 s[16:17], vcc
	s_xor_b64 s[22:23], exec, s[16:17]
	s_cbranch_execz .LBB0_1403
	v_readlane_b32 s16, v247, 11
	v_readlane_b32 s17, v247, 12
	s_waitcnt lgkmcnt(0)
	s_nop 3
	global_load_dword v0, v173, s[16:17] sc1
	s_waitcnt vmcnt(0)
	v_cmp_eq_u32_e32 vcc, v0, v1
	s_and_saveexec_b64 s[28:29], vcc
	s_cbranch_execz .LBB0_1402
	s_mov_b32 s6, 1
	s_mov_b64 s[36:37], 0
	s_branch .LBB0_1393

; __device__ __forceinline__ unsigned xb_add(unsigned* p, unsigned v) { return __hip_atomic_fetch_add(p, v, __ATOMIC_RELAXED, __HIP_MEMORY_SCOPE_AGENT); }
; __device__ __forceinline__ void xcd_barrier(const XcdBarrier& b) {
;     ...
;             __builtin_amdgcn_fence(__ATOMIC_ACQUIRE, "agent");
;             xb_add(&bar[XB_XGEN(b.x)], 1u);
;             asm volatile("s_waitcnt vmcnt(0)" ::: "memory");
.LBB0_1420:
	s_or_b64 exec, exec, s[22:23]
	s_mov_b64 s[22:23], exec
	v_mbcnt_lo_u32_b32 v0, s22, 0
	v_mbcnt_hi_u32_b32 v0, s23, v0
	v_cmp_eq_u32_e32 vcc, 0, v0
	s_waitcnt vmcnt(0)
	s_and_saveexec_b64 s[28:29], vcc
	s_cbranch_execz .LBB0_1422
	s_bcnt1_i32_b64 s6, s[22:23]
	v_readlane_b32 s16, v247, 11
	v_mov_b32_e32 v0, s6
	v_readlane_b32 s17, v247, 12
	s_nop 4
	global_atomic_add v173, v0, s[16:17]

; __device__ __forceinline__ unsigned xb_ld(unsigned* p)              { return __hip_atomic_load(p, __ATOMIC_RELAXED, __HIP_MEMORY_SCOPE_AGENT); }
; __device__ __forceinline__ unsigned xb_add(unsigned* p, unsigned v) { return __hip_atomic_fetch_add(p, v, __ATOMIC_RELAXED, __HIP_MEMORY_SCOPE_AGENT); }
; #define XB_SPIN(cond, bar) do { unsigned _sp = 0; while (cond) { __builtin_amdgcn_s_sleep(1); \
;     if ((++_sp & 255u) == 0u) { if (xb_ld(&(bar)[XB_TMO])) break; if (_sp > XB_SPIN_CAP) { atomicAdd(&(bar)[XB_TMO], 1u); break; } } } } while (0)
; __device__ __forceinline__ void xcd_barrier(const XcdBarrier& b) {
;     ...
;         unsigned nloc = b.st[0], nx = b.st[1];
;         if (nloc == 0u) { xcd_barrier_complete(bar, b.x, nloc, nx); b.st[0] = nloc; b.st[1] = nx; }
;         const unsigned old = xb_add(&bar[XB_XSUB(b.x)], 1u);
;         const unsigned gen = old / nloc;
;         if (old + 1u == (gen + 1u) * nloc) {
;             __builtin_amdgcn_fence(__ATOMIC_RELEASE, "agent");
;             asm volatile("s_waitcnt vmcnt(0)" ::: "memory");
;             const unsigned og = xb_add(&bar[XB_TOP], 1u);
;             const unsigned tg = og / nx;
;             if (og + 1u == (tg + 1u) * nx) xb_add(&bar[XB_TOPGEN], 1u);
;             else XB_SPIN(xb_ld(&bar[XB_TOPGEN]) == tg, bar);
;             __builtin_amdgcn_fence(__ATOMIC_ACQUIRE, "agent");
;             xb_add(&bar[XB_XGEN(b.x)], 1u);
;             asm volatile("s_waitcnt vmcnt(0)" ::: "memory");
;         } else {
;             XB_SPIN(xb_ld(&bar[XB_XGEN(b.x)]) == gen, bar);
;             __builtin_amdgcn_fence(__ATOMIC_ACQUIRE, "agent");
.LBB0_1541:
	s_or_b64 exec, exec, s[22:23]
	buffer_inv sc1
	v_cvt_f32_u32_e32 v4, v2
	s_waitcnt vmcnt(1)
	v_readfirstlane_b32 s11, v3
	v_sub_u32_e32 v3, 0, v2
	v_rcp_iflag_f32_e32 v4, v4
	v_add_u32_e32 v5, s11, v1
	v_mul_f32_e32 v4, 0x4f7ffffe, v4
	v_cvt_u32_f32_e32 v4, v4
	v_mul_lo_u32 v1, v3, v4
	v_mul_hi_u32 v1, v4, v1
	v_add_u32_e32 v1, v4, v1
	v_mul_hi_u32 v1, v5, v1
	v_mul_lo_u32 v3, v1, v2
	v_sub_u32_e32 v3, v5, v3
	v_add_u32_e32 v4, 1, v1
	v_cmp_ge_u32_e32 vcc, v3, v2
	s_nop 1
	v_cndmask_b32_e32 v1, v1, v4, vcc
	v_sub_u32_e32 v4, v3, v2
	v_cndmask_b32_e32 v3, v3, v4, vcc
	v_add_u32_e32 v4, 1, v1
	v_cmp_ge_u32_e32 vcc, v3, v2
	v_add_u32_e32 v3, 1, v5
	s_nop 0
	v_cndmask_b32_e32 v1, v1, v4, vcc
	v_mul_lo_u32 v4, v2, v1
	v_add_u32_e32 v2, v4, v2
	v_cmp_ne_u32_e32 vcc, v3, v2
	s_and_saveexec_b64 s[12:13], vcc
	s_xor_b64 s[22:23], exec, s[12:13]
	s_cbranch_execz .LBB0_1555
	v_readlane_b32 s12, v247, 11
	v_readlane_b32 s13, v247, 12
	s_waitcnt lgkmcnt(0)
	s_nop 3
	global_load_dword v0, v173, s[12:13] sc1
	s_waitcnt vmcnt(0)
	v_cmp_eq_u32_e32 vcc, v0, v1
	s_and_saveexec_b64 s[36:37], vcc
	s_cbranch_execz .LBB0_1554
	s_mov_b32 s11, 1
	s_mov_b64 s[40:41], 0
	s_branch .LBB0_1545

; __device__ __forceinline__ unsigned xb_ld(unsigned* p)              { return __hip_atomic_load(p, __ATOMIC_RELAXED, __HIP_MEMORY_SCOPE_AGENT); }
; #define XB_SPIN(cond, bar) do { unsigned _sp = 0; while (cond) { __builtin_amdgcn_s_sleep(1); \
;     if ((++_sp & 255u) == 0u) { if (xb_ld(&(bar)[XB_TMO])) break; if (_sp > XB_SPIN_CAP) { atomicAdd(&(bar)[XB_TMO], 1u); break; } } } } while (0)
; __device__ __forceinline__ void xcd_barrier(const XcdBarrier& b) {
;     ...
;             XB_SPIN(xb_ld(&bar[XB_XGEN(b.x)]) == gen, bar);
;             __builtin_amdgcn_fence(__ATOMIC_ACQUIRE, "agent");
;             asm volatile("s_waitcnt vmcnt(0)" ::: "memory");
.LBB0_1554:
	s_or_b64 exec, exec, s[36:37]
	s_waitcnt vmcnt(0)
	s_waitcnt vmcnt(0)

; __device__ __forceinline__ unsigned xb_ld(unsigned* p)              { return __hip_atomic_load(p, __ATOMIC_RELAXED, __HIP_MEMORY_SCOPE_AGENT); }
; __device__ __forceinline__ unsigned xb_add(unsigned* p, unsigned v) { return __hip_atomic_fetch_add(p, v, __ATOMIC_RELAXED, __HIP_MEMORY_SCOPE_AGENT); }
; #define XB_SPIN(cond, bar) do { unsigned _sp = 0; while (cond) { __builtin_amdgcn_s_sleep(1); \
;     if ((++_sp & 255u) == 0u) { if (xb_ld(&(bar)[XB_TMO])) break; if (_sp > XB_SPIN_CAP) { atomicAdd(&(bar)[XB_TMO], 1u); break; } } } } while (0)
; __device__ __forceinline__ void xcd_barrier(const XcdBarrier& b) {
;     ...
;         unsigned nloc = b.st[0], nx = b.st[1];
;         if (nloc == 0u) { xcd_barrier_complete(bar, b.x, nloc, nx); b.st[0] = nloc; b.st[1] = nx; }
;         const unsigned old = xb_add(&bar[XB_XSUB(b.x)], 1u);
;         const unsigned gen = old / nloc;
;         if (old + 1u == (gen + 1u) * nloc) {
;             __builtin_amdgcn_fence(__ATOMIC_RELEASE, "agent");
;             asm volatile("s_waitcnt vmcnt(0)" ::: "memory");
;             const unsigned og = xb_add(&bar[XB_TOP], 1u);
;             const unsigned tg = og / nx;
;             if (og + 1u == (tg + 1u) * nx) xb_add(&bar[XB_TOPGEN], 1u);
;             else XB_SPIN(xb_ld(&bar[XB_TOPGEN]) == tg, bar);
;             __builtin_amdgcn_fence(__ATOMIC_ACQUIRE, "agent");
;             xb_add(&bar[XB_XGEN(b.x)], 1u);
;             asm volatile("s_waitcnt vmcnt(0)" ::: "memory");
;         } else {
;             XB_SPIN(xb_ld(&bar[XB_XGEN(b.x)]) == gen, bar);
;             __builtin_amdgcn_fence(__ATOMIC_ACQUIRE, "agent");
.LBB0_2162:
	s_or_b64 exec, exec, s[22:23]
	buffer_inv sc1
	v_cvt_f32_u32_e32 v4, v2
	s_waitcnt vmcnt(1)
	v_readfirstlane_b32 s6, v3
	v_sub_u32_e32 v3, 0, v2
	v_rcp_iflag_f32_e32 v4, v4
	v_add_u32_e32 v5, s6, v1
	v_mul_f32_e32 v4, 0x4f7ffffe, v4
	v_cvt_u32_f32_e32 v4, v4
	v_mul_lo_u32 v1, v3, v4
	v_mul_hi_u32 v1, v4, v1
	v_add_u32_e32 v1, v4, v1
	v_mul_hi_u32 v1, v5, v1
	v_mul_lo_u32 v3, v1, v2
	v_sub_u32_e32 v3, v5, v3
	v_add_u32_e32 v4, 1, v1
	v_cmp_ge_u32_e32 vcc, v3, v2
	s_nop 1
	v_cndmask_b32_e32 v1, v1, v4, vcc
	v_sub_u32_e32 v4, v3, v2
	v_cndmask_b32_e32 v3, v3, v4, vcc
	v_add_u32_e32 v4, 1, v1
	v_cmp_ge_u32_e32 vcc, v3, v2
	v_add_u32_e32 v3, 1, v5
	s_nop 0
	v_cndmask_b32_e32 v1, v1, v4, vcc
	v_mul_lo_u32 v4, v2, v1
	v_add_u32_e32 v2, v4, v2
	v_cmp_ne_u32_e32 vcc, v3, v2
	s_and_saveexec_b64 s[14:15], vcc
	s_xor_b64 s[22:23], exec, s[14:15]
	s_cbranch_execz .LBB0_2176
	v_readlane_b32 s14, v247, 11
	v_readlane_b32 s15, v247, 12
	s_waitcnt lgkmcnt(0)
	s_nop 3
	global_load_dword v0, v173, s[14:15] sc1
	s_waitcnt vmcnt(0)
	v_cmp_eq_u32_e32 vcc, v0, v1
	s_and_saveexec_b64 s[26:27], vcc
	s_cbranch_execz .LBB0_2175
	s_mov_b32 s6, 1
	s_mov_b64 s[28:29], 0
	s_branch .LBB0_2166

; __device__ __forceinline__ unsigned xb_ld(unsigned* p)              { return __hip_atomic_load(p, __ATOMIC_RELAXED, __HIP_MEMORY_SCOPE_AGENT); }
; #define XB_SPIN(cond, bar) do { unsigned _sp = 0; while (cond) { __builtin_amdgcn_s_sleep(1); \
;     if ((++_sp & 255u) == 0u) { if (xb_ld(&(bar)[XB_TMO])) break; if (_sp > XB_SPIN_CAP) { atomicAdd(&(bar)[XB_TMO], 1u); break; } } } } while (0)
; __device__ __forceinline__ void xcd_barrier(const XcdBarrier& b) {
;     ...
;             XB_SPIN(xb_ld(&bar[XB_XGEN(b.x)]) == gen, bar);
;             __builtin_amdgcn_fence(__ATOMIC_ACQUIRE, "agent");
;             asm volatile("s_waitcnt vmcnt(0)" ::: "memory");
.LBB0_2175:
	s_or_b64 exec, exec, s[26:27]
	s_waitcnt vmcnt(0)
	s_waitcnt vmcnt(0)

; __device__ __forceinline__ unsigned xb_add(unsigned* p, unsigned v) { return __hip_atomic_fetch_add(p, v, __ATOMIC_RELAXED, __HIP_MEMORY_SCOPE_AGENT); }
; __device__ __forceinline__ void xcd_barrier(const XcdBarrier& b) {
;     ...
;             __builtin_amdgcn_fence(__ATOMIC_ACQUIRE, "agent");
;             xb_add(&bar[XB_XGEN(b.x)], 1u);
;             asm volatile("s_waitcnt vmcnt(0)" ::: "memory");
.LBB0_2193:
	s_or_b64 exec, exec, s[22:23]
	s_mov_b64 s[22:23], exec
	v_mbcnt_lo_u32_b32 v0, s22, 0
	v_mbcnt_hi_u32_b32 v0, s23, v0
	v_cmp_eq_u32_e32 vcc, 0, v0
	s_waitcnt vmcnt(0)
	s_and_saveexec_b64 s[26:27], vcc
	s_cbranch_execz .LBB0_2195
	s_bcnt1_i32_b64 s6, s[22:23]
	v_readlane_b32 s14, v247, 11
	v_mov_b32_e32 v0, s6
	v_readlane_b32 s15, v247, 12
	s_nop 4
	global_atomic_add v173, v0, s[14:15]

; __device__ __forceinline__ unsigned xb_ld(unsigned* p)              { return __hip_atomic_load(p, __ATOMIC_RELAXED, __HIP_MEMORY_SCOPE_AGENT); }
; __device__ __forceinline__ unsigned xb_add(unsigned* p, unsigned v) { return __hip_atomic_fetch_add(p, v, __ATOMIC_RELAXED, __HIP_MEMORY_SCOPE_AGENT); }
; #define XB_SPIN(cond, bar) do { unsigned _sp = 0; while (cond) { __builtin_amdgcn_s_sleep(1); \
;     if ((++_sp & 255u) == 0u) { if (xb_ld(&(bar)[XB_TMO])) break; if (_sp > XB_SPIN_CAP) { atomicAdd(&(bar)[XB_TMO], 1u); break; } } } } while (0)
; __device__ __forceinline__ void xcd_barrier(const XcdBarrier& b) {
;     ...
;         unsigned nloc = b.st[0], nx = b.st[1];
;         if (nloc == 0u) { xcd_barrier_complete(bar, b.x, nloc, nx); b.st[0] = nloc; b.st[1] = nx; }
;         const unsigned old = xb_add(&bar[XB_XSUB(b.x)], 1u);
;         const unsigned gen = old / nloc;
;         if (old + 1u == (gen + 1u) * nloc) {
;             __builtin_amdgcn_fence(__ATOMIC_RELEASE, "agent");
;             asm volatile("s_waitcnt vmcnt(0)" ::: "memory");
;             const unsigned og = xb_add(&bar[XB_TOP], 1u);
;             const unsigned tg = og / nx;
;             if (og + 1u == (tg + 1u) * nx) xb_add(&bar[XB_TOPGEN], 1u);
;             else XB_SPIN(xb_ld(&bar[XB_TOPGEN]) == tg, bar);
;             __builtin_amdgcn_fence(__ATOMIC_ACQUIRE, "agent");
;             xb_add(&bar[XB_XGEN(b.x)], 1u);
;             asm volatile("s_waitcnt vmcnt(0)" ::: "memory");
;         } else {
;             XB_SPIN(xb_ld(&bar[XB_XGEN(b.x)]) == gen, bar);
;             __builtin_amdgcn_fence(__ATOMIC_ACQUIRE, "agent");
.LBB0_2258:
	s_or_b64 exec, exec, s[22:23]
	buffer_inv sc1
	v_cvt_f32_u32_e32 v4, v2
	s_waitcnt vmcnt(1)
	v_readfirstlane_b32 s11, v3
	v_sub_u32_e32 v3, 0, v2
	v_rcp_iflag_f32_e32 v4, v4
	v_add_u32_e32 v5, s11, v1
	v_mul_f32_e32 v4, 0x4f7ffffe, v4
	v_cvt_u32_f32_e32 v4, v4
	v_mul_lo_u32 v1, v3, v4
	v_mul_hi_u32 v1, v4, v1
	v_add_u32_e32 v1, v4, v1
	v_mul_hi_u32 v1, v5, v1
	v_mul_lo_u32 v3, v1, v2
	v_sub_u32_e32 v3, v5, v3
	v_add_u32_e32 v4, 1, v1
	v_cmp_ge_u32_e32 vcc, v3, v2
	s_nop 1
	v_cndmask_b32_e32 v1, v1, v4, vcc
	v_sub_u32_e32 v4, v3, v2
	v_cndmask_b32_e32 v3, v3, v4, vcc
	v_add_u32_e32 v4, 1, v1
	v_cmp_ge_u32_e32 vcc, v3, v2
	v_add_u32_e32 v3, 1, v5
	s_nop 0
	v_cndmask_b32_e32 v1, v1, v4, vcc
	v_mul_lo_u32 v4, v2, v1
	v_add_u32_e32 v2, v4, v2
	v_cmp_ne_u32_e32 vcc, v3, v2
	s_and_saveexec_b64 s[14:15], vcc
	s_xor_b64 s[22:23], exec, s[14:15]
	s_cbranch_execz .LBB0_2272
	v_readlane_b32 s14, v247, 11
	v_readlane_b32 s15, v247, 12
	s_waitcnt lgkmcnt(0)
	s_nop 3
	global_load_dword v0, v173, s[14:15] sc1
	s_waitcnt vmcnt(0)
	v_cmp_eq_u32_e32 vcc, v0, v1
	s_and_saveexec_b64 s[36:37], vcc
	s_cbranch_execz .LBB0_2271
	s_mov_b32 s11, 1
	s_mov_b64 s[40:41], 0
	s_branch .LBB0_2262

; __device__ __forceinline__ unsigned xb_add(unsigned* p, unsigned v) { return __hip_atomic_fetch_add(p, v, __ATOMIC_RELAXED, __HIP_MEMORY_SCOPE_AGENT); }
; __device__ __forceinline__ void xcd_barrier(const XcdBarrier& b) {
;     ...
;             __builtin_amdgcn_fence(__ATOMIC_ACQUIRE, "agent");
;             xb_add(&bar[XB_XGEN(b.x)], 1u);
;             asm volatile("s_waitcnt vmcnt(0)" ::: "memory");
.LBB0_2289:
	s_or_b64 exec, exec, s[22:23]
	s_mov_b64 s[22:23], exec
	v_mbcnt_lo_u32_b32 v0, s22, 0
	v_mbcnt_hi_u32_b32 v0, s23, v0
	v_cmp_eq_u32_e32 vcc, 0, v0
	s_waitcnt vmcnt(0)
	s_and_saveexec_b64 s[36:37], vcc
	s_cbranch_execz .LBB0_2291
	s_bcnt1_i32_b64 s11, s[22:23]
	v_readlane_b32 s14, v247, 11
	v_mov_b32_e32 v0, s11
	v_readlane_b32 s15, v247, 12
	s_nop 4
	global_atomic_add v173, v0, s[14:15]

; __device__ __forceinline__ unsigned xb_ld(unsigned* p)              { return __hip_atomic_load(p, __ATOMIC_RELAXED, __HIP_MEMORY_SCOPE_AGENT); }
; __device__ __forceinline__ unsigned xb_add(unsigned* p, unsigned v) { return __hip_atomic_fetch_add(p, v, __ATOMIC_RELAXED, __HIP_MEMORY_SCOPE_AGENT); }
; #define XB_SPIN(cond, bar) do { unsigned _sp = 0; while (cond) { __builtin_amdgcn_s_sleep(1); \
;     if ((++_sp & 255u) == 0u) { if (xb_ld(&(bar)[XB_TMO])) break; if (_sp > XB_SPIN_CAP) { atomicAdd(&(bar)[XB_TMO], 1u); break; } } } } while (0)
; __device__ __forceinline__ void xcd_barrier(const XcdBarrier& b) {
;     ...
;         unsigned nloc = b.st[0], nx = b.st[1];
;         if (nloc == 0u) { xcd_barrier_complete(bar, b.x, nloc, nx); b.st[0] = nloc; b.st[1] = nx; }
;         const unsigned old = xb_add(&bar[XB_XSUB(b.x)], 1u);
;         const unsigned gen = old / nloc;
;         if (old + 1u == (gen + 1u) * nloc) {
;             __builtin_amdgcn_fence(__ATOMIC_RELEASE, "agent");
;             asm volatile("s_waitcnt vmcnt(0)" ::: "memory");
;             const unsigned og = xb_add(&bar[XB_TOP], 1u);
;             const unsigned tg = og / nx;
;             if (og + 1u == (tg + 1u) * nx) xb_add(&bar[XB_TOPGEN], 1u);
;             else XB_SPIN(xb_ld(&bar[XB_TOPGEN]) == tg, bar);
;             __builtin_amdgcn_fence(__ATOMIC_ACQUIRE, "agent");
;             xb_add(&bar[XB_XGEN(b.x)], 1u);
;             asm volatile("s_waitcnt vmcnt(0)" ::: "memory");
;         } else {
;             XB_SPIN(xb_ld(&bar[XB_XGEN(b.x)]) == gen, bar);
;             __builtin_amdgcn_fence(__ATOMIC_ACQUIRE, "agent");
.LBB0_2550:
	s_or_b64 exec, exec, s[22:23]
	buffer_inv sc1
	v_cvt_f32_u32_e32 v4, v2
	s_waitcnt vmcnt(1)
	v_readfirstlane_b32 s6, v3
	v_sub_u32_e32 v3, 0, v2
	v_rcp_iflag_f32_e32 v4, v4
	v_add_u32_e32 v5, s6, v1
	v_mul_f32_e32 v4, 0x4f7ffffe, v4
	v_cvt_u32_f32_e32 v4, v4
	v_mul_lo_u32 v1, v3, v4
	v_mul_hi_u32 v1, v4, v1
	v_add_u32_e32 v1, v4, v1
	v_mul_hi_u32 v1, v5, v1
	v_mul_lo_u32 v3, v1, v2
	v_sub_u32_e32 v3, v5, v3
	v_add_u32_e32 v4, 1, v1
	v_cmp_ge_u32_e32 vcc, v3, v2
	s_nop 1
	v_cndmask_b32_e32 v1, v1, v4, vcc
	v_sub_u32_e32 v4, v3, v2
	v_cndmask_b32_e32 v3, v3, v4, vcc
	v_add_u32_e32 v4, 1, v1
	v_cmp_ge_u32_e32 vcc, v3, v2
	v_add_u32_e32 v3, 1, v5
	s_nop 0
	v_cndmask_b32_e32 v1, v1, v4, vcc
	v_mul_lo_u32 v4, v2, v1
	v_add_u32_e32 v2, v4, v2
	v_cmp_ne_u32_e32 vcc, v3, v2
	s_and_saveexec_b64 s[16:17], vcc
	s_xor_b64 s[22:23], exec, s[16:17]
	s_cbranch_execz .LBB0_2564
	v_readlane_b32 s16, v247, 11
	v_readlane_b32 s17, v247, 12
	s_waitcnt lgkmcnt(0)
	s_nop 3
	global_load_dword v0, v173, s[16:17] sc1
	s_waitcnt vmcnt(0)
	v_cmp_eq_u32_e32 vcc, v0, v1
	s_and_saveexec_b64 s[30:31], vcc
	s_cbranch_execz .LBB0_2563
	s_mov_b32 s6, 1
	s_mov_b64 s[36:37], 0
	s_branch .LBB0_2554

; __device__ __forceinline__ unsigned xb_ld(unsigned* p)              { return __hip_atomic_load(p, __ATOMIC_RELAXED, __HIP_MEMORY_SCOPE_AGENT); }
; #define XB_SPIN(cond, bar) do { unsigned _sp = 0; while (cond) { __builtin_amdgcn_s_sleep(1); \
;     if ((++_sp & 255u) == 0u) { if (xb_ld(&(bar)[XB_TMO])) break; if (_sp > XB_SPIN_CAP) { atomicAdd(&(bar)[XB_TMO], 1u); break; } } } } while (0)
; __device__ __forceinline__ void xcd_barrier(const XcdBarrier& b) {
;     ...
;             XB_SPIN(xb_ld(&bar[XB_XGEN(b.x)]) == gen, bar);
;             __builtin_amdgcn_fence(__ATOMIC_ACQUIRE, "agent");
;             asm volatile("s_waitcnt vmcnt(0)" ::: "memory");
.LBB0_2563:
	s_or_b64 exec, exec, s[30:31]
	s_waitcnt vmcnt(0)
	s_waitcnt vmcnt(0)

; __device__ __forceinline__ unsigned xb_add(unsigned* p, unsigned v) { return __hip_atomic_fetch_add(p, v, __ATOMIC_RELAXED, __HIP_MEMORY_SCOPE_AGENT); }
; __device__ __forceinline__ void xcd_barrier(const XcdBarrier& b) {
;     ...
;             __builtin_amdgcn_fence(__ATOMIC_ACQUIRE, "agent");
;             xb_add(&bar[XB_XGEN(b.x)], 1u);
;             asm volatile("s_waitcnt vmcnt(0)" ::: "memory");
.LBB0_2581:
	s_or_b64 exec, exec, s[22:23]
	s_mov_b64 s[22:23], exec
	v_mbcnt_lo_u32_b32 v0, s22, 0
	v_mbcnt_hi_u32_b32 v0, s23, v0
	v_cmp_eq_u32_e32 vcc, 0, v0
	s_waitcnt vmcnt(0)
	s_and_saveexec_b64 s[30:31], vcc
	s_cbranch_execnz .LBB0_2582
	s_getpc_b64 s[98:99]

; __device__ __forceinline__ unsigned xb_ld(unsigned* p)              { return __hip_atomic_load(p, __ATOMIC_RELAXED, __HIP_MEMORY_SCOPE_AGENT); }
; __device__ __forceinline__ unsigned xb_add(unsigned* p, unsigned v) { return __hip_atomic_fetch_add(p, v, __ATOMIC_RELAXED, __HIP_MEMORY_SCOPE_AGENT); }
; #define XB_SPIN(cond, bar) do { unsigned _sp = 0; while (cond) { __builtin_amdgcn_s_sleep(1); \
;     if ((++_sp & 255u) == 0u) { if (xb_ld(&(bar)[XB_TMO])) break; if (_sp > XB_SPIN_CAP) { atomicAdd(&(bar)[XB_TMO], 1u); break; } } } } while (0)
; __device__ __forceinline__ void xcd_barrier(const XcdBarrier& b) {
;     ...
;         unsigned nloc = b.st[0], nx = b.st[1];
;         if (nloc == 0u) { xcd_barrier_complete(bar, b.x, nloc, nx); b.st[0] = nloc; b.st[1] = nx; }
;         const unsigned old = xb_add(&bar[XB_XSUB(b.x)], 1u);
;         const unsigned gen = old / nloc;
;         if (old + 1u == (gen + 1u) * nloc) {
;             __builtin_amdgcn_fence(__ATOMIC_RELEASE, "agent");
;             asm volatile("s_waitcnt vmcnt(0)" ::: "memory");
;             const unsigned og = xb_add(&bar[XB_TOP], 1u);
;             const unsigned tg = og / nx;
;             if (og + 1u == (tg + 1u) * nx) xb_add(&bar[XB_TOPGEN], 1u);
;             else XB_SPIN(xb_ld(&bar[XB_TOPGEN]) == tg, bar);
;             __builtin_amdgcn_fence(__ATOMIC_ACQUIRE, "agent");
;             xb_add(&bar[XB_XGEN(b.x)], 1u);
;             asm volatile("s_waitcnt vmcnt(0)" ::: "memory");
;         } else {
;             XB_SPIN(xb_ld(&bar[XB_XGEN(b.x)]) == gen, bar);
;             __builtin_amdgcn_fence(__ATOMIC_ACQUIRE, "agent");
.LBB0_2618:
	s_or_b64 exec, exec, s[2:3]
	buffer_inv sc1
	v_cvt_f32_u32_e32 v4, v2
	s_waitcnt vmcnt(1)
	v_readfirstlane_b32 s2, v3
	v_sub_u32_e32 v3, 0, v2
	v_rcp_iflag_f32_e32 v4, v4
	v_add_u32_e32 v5, s2, v1
	v_mul_f32_e32 v4, 0x4f7ffffe, v4
	v_cvt_u32_f32_e32 v4, v4
	v_mul_lo_u32 v1, v3, v4
	v_mul_hi_u32 v1, v4, v1
	v_add_u32_e32 v1, v4, v1
	v_mul_hi_u32 v1, v5, v1
	v_mul_lo_u32 v3, v1, v2
	v_sub_u32_e32 v3, v5, v3
	v_add_u32_e32 v4, 1, v1
	v_cmp_ge_u32_e32 vcc, v3, v2
	s_nop 1
	v_cndmask_b32_e32 v1, v1, v4, vcc
	v_sub_u32_e32 v4, v3, v2
	v_cndmask_b32_e32 v3, v3, v4, vcc
	v_add_u32_e32 v4, 1, v1
	v_cmp_ge_u32_e32 vcc, v3, v2
	v_add_u32_e32 v3, 1, v5
	s_nop 0
	v_cndmask_b32_e32 v1, v1, v4, vcc
	v_mul_lo_u32 v4, v2, v1
	v_add_u32_e32 v2, v4, v2
	v_cmp_ne_u32_e32 vcc, v3, v2
	s_and_saveexec_b64 s[2:3], vcc
	s_xor_b64 s[2:3], exec, s[2:3]
	s_cbranch_execz .LBB0_2632
	v_readlane_b32 s4, v247, 11
	s_waitcnt lgkmcnt(0)
	v_mov_b32_e32 v0, 0
	v_readlane_b32 s5, v247, 12
	s_nop 4
	global_load_dword v2, v0, s[4:5] sc1
	s_waitcnt vmcnt(0)
	v_cmp_eq_u32_e32 vcc, v2, v1
	s_and_saveexec_b64 s[4:5], vcc
	s_cbranch_execz .LBB0_2631
	s_mov_b32 s16, 1
	s_mov_b64 s[6:7], 0
	s_branch .LBB0_2622

; __device__ __forceinline__ unsigned xb_ld(unsigned* p)              { return __hip_atomic_load(p, __ATOMIC_RELAXED, __HIP_MEMORY_SCOPE_AGENT); }
; #define XB_SPIN(cond, bar) do { unsigned _sp = 0; while (cond) { __builtin_amdgcn_s_sleep(1); \
;     if ((++_sp & 255u) == 0u) { if (xb_ld(&(bar)[XB_TMO])) break; if (_sp > XB_SPIN_CAP) { atomicAdd(&(bar)[XB_TMO], 1u); break; } } } } while (0)
; __device__ __forceinline__ void xcd_barrier(const XcdBarrier& b) {
;     ...
;             XB_SPIN(xb_ld(&bar[XB_XGEN(b.x)]) == gen, bar);
;             __builtin_amdgcn_fence(__ATOMIC_ACQUIRE, "agent");
;             asm volatile("s_waitcnt vmcnt(0)" ::: "memory");
.LBB0_2631:
	s_or_b64 exec, exec, s[4:5]
	s_waitcnt vmcnt(0)
	s_waitcnt vmcnt(0)

; __device__ __forceinline__ unsigned xb_add(unsigned* p, unsigned v) { return __hip_atomic_fetch_add(p, v, __ATOMIC_RELAXED, __HIP_MEMORY_SCOPE_AGENT); }
; __device__ __forceinline__ void xcd_barrier(const XcdBarrier& b) {
;     ...
;             __builtin_amdgcn_fence(__ATOMIC_ACQUIRE, "agent");
;             xb_add(&bar[XB_XGEN(b.x)], 1u);
;             asm volatile("s_waitcnt vmcnt(0)" ::: "memory");
.LBB0_2649:
	s_or_b64 exec, exec, s[2:3]
	s_mov_b64 s[2:3], exec
	v_mbcnt_lo_u32_b32 v0, s2, 0
	v_mbcnt_hi_u32_b32 v0, s3, v0
	v_cmp_eq_u32_e32 vcc, 0, v0
	s_waitcnt vmcnt(0)
	s_and_saveexec_b64 s[4:5], vcc
	s_cbranch_execz .LBB0_2651
	s_bcnt1_i32_b64 s2, s[2:3]
	v_mov_b32_e32 v1, s2
	v_readlane_b32 s2, v247, 11
	v_mov_b32_e32 v0, 0
	v_readlane_b32 s3, v247, 12
	s_nop 4
	global_atomic_add v0, v1, s[2:3]
